# gate-up tiles: row sum-of-squares partials for the SwiGLU epilogue prefetched by LDS-DMA during the first K iteration (last 4 KiB of LDS), epilogue reads them with ds_read_b128 instead of 8 global loa
# speedup vs baseline: 1.0093x; 1.0093x over previous
; #define PG8_STAGE(bufoff, gbase, voff) do { _Pragma("unroll") for (int _i = 0; _i < 2; ++_i) { \
;         const unsigned _m0 = ldsb + (unsigned)((bufoff) + _i * 8192); const char* _gb = (const char*)(gbase); \
;         asm volatile("s_mov_b32 m0, %0\n\ts_nop 0\n\tglobal_load_lds_dwordx4 %1, %2" :: "s"(_m0), "v"((voff)[_i]), "s"(_gb) : "m0", "memory"); } } while (0)
; #define PG8_LDA(dst, b, h) do { _Pragma("unroll") for (int m = 0; m < 4; ++m) _Pragma("unroll") for (int k = 0; k < 2; ++k) dst[m][k] = *(const LAS bf16x8*)(lds + PG8_SA(b, h) + aoff + m * 2048 + k * 1024); } while (0)
; #define PG8_LDB(dst, b, h) do { _Pragma("unroll") for (int n = 0; n < 2; ++n) _Pragma("unroll") for (int k = 0; k < 2; ++k) dst[n][k] = *(const LAS bf16x8*)(lds + PG8_SB(b, h) + boff + n * 2048 + k * 1024); } while (0)
; #define PG8_MMA(ai, bj, At, Bt) do { __builtin_amdgcn_s_setprio(1); _Pragma("unroll") for (int m = 0; m < 4; ++m) _Pragma("unroll") for (int n = 0; n < 2; ++n) _Pragma("unroll") for (int k = 0; k < 2; ++k) \
;         acc[ai][bj][m][n] = __builtin_amdgcn_mfma_f32_16x16x32_bf16(Bt[n][k], At[m][k], acc[ai][bj][m][n], 0, 0, 0); __builtin_amdgcn_s_setprio(0); } while (0)
; #define PG8_WAIT_V(n) asm volatile("s_waitcnt vmcnt(" #n ")" ::: "memory")
; #define PG8_WAIT_L(n) asm volatile("s_waitcnt lgkmcnt(" #n ")" ::: "memory")
; #define PG8_BAR __builtin_amdgcn_s_barrier()
; __device__ __forceinline__ void rstd8(const float* ss, int row0, float (&rs)[2][4]) {
;     f32x4 p[2][4];
; #pragma unroll
;     for (int ai = 0; ai < 2; ++ai)
; #pragma unroll
;         for (int m = 0; m < 4; ++m) p[ai][m] = *(const f32x4*)(ss + 4 * (size_t)(row0 + ai * HALF + m * 16));
; template <class Epi, bool ALIGN_EPI>
; __device__ __forceinline__ void gemm_phase(LAS unsigned char* lds, const Gemm g, const StaticOrder& S, const Epi& E) {
;     ...
;             PG8_LDB(B0, 0, 0); PG8_LDB(B1, 0, 1); PG8_SCHED; PG8_LDA(At, 0, 0); PG8_STAGE(PG8_SA(1, 1), a1 + hstepA, voffA);
;             PG8_WAIT_V(8); PG8_WAIT_L(0); PG8_BAR; PG8_MMA(0, 0, At, B0); PG8_MMA(0, 1, At, B1); PG8_BAR; PG8_SCHED;
;             PG8_LDA(At, 0, 1); PG8_STAGE(PG8_SB(0, 0), b2, voffB); PG8_STAGE(PG8_SB(0, 1), b2 + hstepB, voffB); PG8_STAGE(PG8_SA(0, 0), a2, voffA);
;             PG8_WAIT_V(8); PG8_WAIT_L(0); PG8_BAR; PG8_MMA(1, 0, At, B0); PG8_MMA(1, 1, At, B1); PG8_BAR; PG8_SCHED;
.LBB0_305:
	s_add_u32 s41, s56, 0x100
	s_addc_u32 s49, s57, 0
	s_add_u32 s92, s58, 0x40080
	s_addc_u32 s93, s59, 0
	s_mov_b32 s50, -2
	s_add_u32 s30, s92, 0xfffc0080
	s_addc_u32 s31, s93, -1
	s_cmp_eq_u32 s50, 12
	s_cselect_b32 s60, s5, s30
	s_cselect_b32 s61, s4, s31
	s_cselect_b32 s58, s37, s41
	s_cselect_b32 s59, s35, s49
	s_add_u32 s56, s60, 0x80
	s_addc_u32 s57, s61, 0
	s_mov_b32 m0, s67
	s_nop 0
	global_load_lds_dwordx4 v0, s[92:93]
	s_nop 0
	s_mov_b32 m0, s65
	s_nop 0
	global_load_lds_dwordx4 v181, s[92:93]
	s_waitcnt vmcnt(8)
	s_waitcnt lgkmcnt(0)
	s_setprio 1
	s_barrier
	v_mfma_f32_16x16x32_bf16 v[142:145], v[74:77], v[162:165], 0
	v_mfma_f32_16x16x32_bf16 v[142:145], v[94:97], v[166:169], v[142:145]
	v_mfma_f32_16x16x32_bf16 v[138:141], v[114:117], v[162:165], 0
	v_mfma_f32_16x16x32_bf16 v[138:141], v[134:137], v[166:169], v[138:141]
	v_mfma_f32_16x16x32_bf16 v[130:133], v[146:149], v[162:165], 0
	v_mfma_f32_16x16x32_bf16 v[130:133], v[150:153], v[166:169], v[130:133]
	v_mfma_f32_16x16x32_bf16 v[126:129], v[154:157], v[162:165], 0
	v_mfma_f32_16x16x32_bf16 v[126:129], v[158:161], v[166:169], v[126:129]
	v_mfma_f32_16x16x32_bf16 v[106:109], v[154:157], v[170:173], 0
	v_mfma_f32_16x16x32_bf16 v[106:109], v[158:161], v[174:177], v[106:109]
	v_mfma_f32_16x16x32_bf16 v[110:113], v[146:149], v[170:173], 0
	v_mfma_f32_16x16x32_bf16 v[110:113], v[150:153], v[174:177], v[110:113]
	v_mfma_f32_16x16x32_bf16 v[118:121], v[114:117], v[170:173], 0
	v_mfma_f32_16x16x32_bf16 v[118:121], v[134:137], v[174:177], v[118:121]
	v_mfma_f32_16x16x32_bf16 v[122:125], v[74:77], v[170:173], 0
	v_mfma_f32_16x16x32_bf16 v[122:125], v[94:97], v[174:177], v[122:125]
	v_mfma_f32_16x16x32_bf16 v[102:105], v[74:77], v[188:191], 0
	v_mfma_f32_16x16x32_bf16 v[102:105], v[94:97], v[202:205], v[102:105]
	v_mfma_f32_16x16x32_bf16 v[98:101], v[114:117], v[188:191], 0
	v_mfma_f32_16x16x32_bf16 v[98:101], v[134:137], v[202:205], v[98:101]
	v_mfma_f32_16x16x32_bf16 v[90:93], v[146:149], v[188:191], 0
	v_mfma_f32_16x16x32_bf16 v[90:93], v[150:153], v[202:205], v[90:93]
	v_mfma_f32_16x16x32_bf16 v[86:89], v[154:157], v[188:191], 0
	v_mfma_f32_16x16x32_bf16 v[86:89], v[158:161], v[202:205], v[86:89]
	v_mfma_f32_16x16x32_bf16 v[66:69], v[154:157], v[206:209], 0
	v_mfma_f32_16x16x32_bf16 v[66:69], v[158:161], v[210:213], v[66:69]
	v_mfma_f32_16x16x32_bf16 v[70:73], v[146:149], v[206:209], 0
	v_mfma_f32_16x16x32_bf16 v[70:73], v[150:153], v[210:213], v[70:73]
	v_mfma_f32_16x16x32_bf16 v[78:81], v[114:117], v[206:209], 0
	v_mfma_f32_16x16x32_bf16 v[78:81], v[134:137], v[210:213], v[78:81]
	v_mfma_f32_16x16x32_bf16 v[82:85], v[74:77], v[206:209], 0
	v_mfma_f32_16x16x32_bf16 v[82:85], v[94:97], v[210:213], v[82:85]
	s_barrier
	s_setprio 0
	v_mbcnt_lo_u32_b32 v178, -1, 0
	v_mbcnt_hi_u32_b32 v178, -1, v178
	s_lshl_b32 s90, s54, 8
	s_add_i32 s90, s90, s89
	s_lshl_b32 s91, s89, 4
	s_add_i32 s91, s91, 0x23000
	v_add_lshl_u32 v178, v178, s90, 4
	s_mov_b32 m0, s91
	s_nop 0
	global_load_lds_dwordx4 v178, s[24:25]
	global_load_lds_dwordx4 v178, s[24:25] offset:2048
	ds_read_b128 v[162:165], v186 offset:16384
	ds_read_b128 v[166:169], v186 offset:17408
	ds_read_b128 v[170:173], v186 offset:18432
	ds_read_b128 v[174:177], v186 offset:19456
	ds_read_b128 v[188:191], v186 offset:20480
	ds_read_b128 v[202:205], v186 offset:21504
	ds_read_b128 v[206:209], v186 offset:22528
	ds_read_b128 v[210:213], v186 offset:23552
	s_mov_b32 m0, s29
	s_nop 0
	global_load_lds_dwordx4 v180, s[58:59]
	s_add_u32 s30, s58, 0x40000
	s_mov_b32 m0, s42
	s_nop 0
	global_load_lds_dwordx4 v182, s[58:59]
	s_addc_u32 s31, s59, 0
	s_mov_b32 m0, s43
	s_nop 0
	global_load_lds_dwordx4 v180, s[30:31]
	s_nop 0
	s_mov_b32 m0, s44
	s_nop 0
	global_load_lds_dwordx4 v182, s[30:31]
	s_nop 0
	s_mov_b32 m0, s15
	s_nop 0
	global_load_lds_dwordx4 v0, s[60:61]
	s_nop 0
	s_mov_b32 m0, s45
	s_nop 0
	global_load_lds_dwordx4 v181, s[60:61]
	s_mul_i32 s4, s85, s27
	s_mul_hi_u32 s5, s85, s87
	s_add_i32 s5, s5, s4
	s_mul_i32 s4, s85, s87
	s_add_u32 s4, s4, s16
	s_addc_u32 s5, s5, s68
	v_mov_b64_e32 v[192:193], s[46:47]
	v_cmp_lt_i64_e64 s[8:9], s[4:5], v[192:193]
	s_ashr_i32 s5, s4, 31
	s_lshr_b32 s5, s5, 29
	s_add_i32 s5, s4, s5
	s_ashr_i32 s90, s5, 3
	s_and_b32 s5, s5, -8
	s_sub_i32 s4, s4, s5
	s_lshr_b32 s5, s4, 31
	s_or_b32 s5, s78, s5
	s_mul_i32 s4, s5, s4
	s_add_i32 s4, s4, s90
	s_abs_i32 s90, s4
	v_readlane_b32 s91, v254, 48
	s_mul_hi_u32 s91, s90, s91
	s_mul_i32 s34, s91, s26
	s_sub_i32 s90, s90, s34
	s_ashr_i32 s5, s4, 31
	s_add_i32 s34, s91, 1
	s_sub_i32 s35, s90, s26
	s_cmp_ge_u32 s90, s26
	s_cselect_b32 s91, s34, s91
	s_cselect_b32 s90, s35, s90
	s_waitcnt vmcnt(8)
	s_waitcnt lgkmcnt(0)
	s_setprio 1
	s_barrier
; #define PG8_STAGE(bufoff, gbase, voff) do { _Pragma("unroll") for (int _i = 0; _i < 2; ++_i) { \
;         const unsigned _m0 = ldsb + (unsigned)((bufoff) + _i * 8192); const char* _gb = (const char*)(gbase); \
;         asm volatile("s_mov_b32 m0, %0\n\ts_nop 0\n\tglobal_load_lds_dwordx4 %1, %2" :: "s"(_m0), "v"((voff)[_i]), "s"(_gb) : "m0", "memory"); } } while (0)
; #define PG8_LDA(dst, b, h) do { _Pragma("unroll") for (int m = 0; m < 4; ++m) _Pragma("unroll") for (int k = 0; k < 2; ++k) dst[m][k] = *(const LAS bf16x8*)(lds + PG8_SA(b, h) + aoff + m * 2048 + k * 1024); } while (0)
; #define PG8_LDB(dst, b, h) do { _Pragma("unroll") for (int n = 0; n < 2; ++n) _Pragma("unroll") for (int k = 0; k < 2; ++k) dst[n][k] = *(const LAS bf16x8*)(lds + PG8_SB(b, h) + boff + n * 2048 + k * 1024); } while (0)
; #define PG8_WAIT_V(n) asm volatile("s_waitcnt vmcnt(" #n ")" ::: "memory")
;     __device__ bool next(int i, Unit& u) const {
;     ...
;         int wgid = (int)L; { const int q = nwg / NXCD, r = nwg % NXCD, xcd = wgid % NXCD, off = wgid / NXCD; wgid = (xcd < r ? xcd * (q + 1) : r * (q + 1) + (xcd - r) * q) + off; }
;         const int nig = WGM * nN, gid = wgid / nig, fm = gid * WGM, gsz = (nM - fm) < WGM ? (nM - fm) : WGM;
;         u.pm = fm + ((wgid % nig) % gsz); u.pn = (wgid % nig) / gsz; return true;
; template <class Epi, bool ALIGN_EPI>
; __device__ __forceinline__ void gemm_phase(LAS unsigned char* lds, const Gemm g, const StaticOrder& S, const Epi& E) {
;     ...
;             PG8_WAIT_V(8); PG8_WAIT_L(0); PG8_BAR; PG8_MMA(0, 0, At, B0); PG8_MMA(0, 1, At, B1); PG8_BAR; PG8_SCHED;
;             PG8_LDA(At, 0, 1); PG8_STAGE(PG8_SB(0, 0), b2, voffB); PG8_STAGE(PG8_SB(0, 1), b2 + hstepB, voffB); PG8_STAGE(PG8_SA(0, 0), a2, voffA);
;             PG8_WAIT_V(8); PG8_WAIT_L(0); PG8_BAR; PG8_MMA(1, 0, At, B0); PG8_MMA(1, 1, At, B1); PG8_BAR; PG8_SCHED;
;             PG8_LDB(B0, 1, 0); PG8_LDB(B1, 1, 1); PG8_SCHED; PG8_LDA(At, 1, 0); PG8_STAGE(PG8_SA(0, 1), a2 + hstepA, voffA);
;             PG8_WAIT_V(8); PG8_WAIT_L(0); PG8_BAR; PG8_MMA(0, 0, At, B0); PG8_MMA(0, 1, At, B1); PG8_BAR; PG8_SCHED;
;             PG8_LDA(At, 1, 1); PG8_STAGE(PG8_SB(1, 0), b3, voffB); PG8_STAGE(PG8_SB(1, 1), b3 + hstepB, voffB); PG8_STAGE(PG8_SA(1, 0), a3, voffA);
;             PG8_WAIT_V(8); PG8_WAIT_L(0); PG8_BAR; PG8_MMA(1, 0, At, B0); PG8_MMA(1, 1, At, B1); PG8_BAR; PG8_SCHED;
	v_mfma_f32_16x16x32_bf16 v[62:65], v[74:77], v[162:165], 0
	v_mfma_f32_16x16x32_bf16 v[62:65], v[94:97], v[166:169], v[62:65]
	v_mfma_f32_16x16x32_bf16 v[58:61], v[114:117], v[162:165], 0
	v_mfma_f32_16x16x32_bf16 v[58:61], v[134:137], v[166:169], v[58:61]
	v_mfma_f32_16x16x32_bf16 v[54:57], v[146:149], v[162:165], 0
	v_mfma_f32_16x16x32_bf16 v[54:57], v[150:153], v[166:169], v[54:57]
	v_mfma_f32_16x16x32_bf16 v[50:53], v[154:157], v[162:165], 0
	v_mfma_f32_16x16x32_bf16 v[50:53], v[158:161], v[166:169], v[50:53]
	v_mfma_f32_16x16x32_bf16 v[34:37], v[154:157], v[170:173], 0
	v_mfma_f32_16x16x32_bf16 v[34:37], v[158:161], v[174:177], v[34:37]
	v_mfma_f32_16x16x32_bf16 v[38:41], v[146:149], v[170:173], 0
	v_mfma_f32_16x16x32_bf16 v[38:41], v[150:153], v[174:177], v[38:41]
	v_mfma_f32_16x16x32_bf16 v[42:45], v[114:117], v[170:173], 0
	v_mfma_f32_16x16x32_bf16 v[42:45], v[134:137], v[174:177], v[42:45]
	v_mfma_f32_16x16x32_bf16 v[46:49], v[74:77], v[170:173], 0
	v_mfma_f32_16x16x32_bf16 v[46:49], v[94:97], v[174:177], v[46:49]
	v_mfma_f32_16x16x32_bf16 v[30:33], v[74:77], v[188:191], 0
	v_mfma_f32_16x16x32_bf16 v[30:33], v[94:97], v[202:205], v[30:33]
	v_mfma_f32_16x16x32_bf16 v[26:29], v[114:117], v[188:191], 0
	v_mfma_f32_16x16x32_bf16 v[26:29], v[134:137], v[202:205], v[26:29]
	v_mfma_f32_16x16x32_bf16 v[22:25], v[146:149], v[188:191], 0
	v_mfma_f32_16x16x32_bf16 v[22:25], v[150:153], v[202:205], v[22:25]
	v_mfma_f32_16x16x32_bf16 v[18:21], v[154:157], v[188:191], 0
	v_mfma_f32_16x16x32_bf16 v[18:21], v[158:161], v[202:205], v[18:21]
	v_mfma_f32_16x16x32_bf16 v[2:5], v[154:157], v[206:209], 0
	v_mfma_f32_16x16x32_bf16 v[2:5], v[158:161], v[210:213], v[2:5]
	v_mfma_f32_16x16x32_bf16 v[6:9], v[146:149], v[206:209], 0
	v_mfma_f32_16x16x32_bf16 v[6:9], v[150:153], v[210:213], v[6:9]
	v_mfma_f32_16x16x32_bf16 v[10:13], v[114:117], v[206:209], 0
	v_mfma_f32_16x16x32_bf16 v[10:13], v[134:137], v[210:213], v[10:13]
	v_mfma_f32_16x16x32_bf16 v[14:17], v[74:77], v[206:209], 0
	v_mfma_f32_16x16x32_bf16 v[14:17], v[94:97], v[210:213], v[14:17]
	s_barrier
	s_setprio 0
	v_add_u32_e32 v134, 0x18000, v185
	v_add_u32_e32 v158, 0x1c000, v185
	ds_read_b128 v[74:77], v134
	ds_read_b128 v[94:97], v134 offset:1024
	ds_read_b128 v[114:117], v134 offset:2048
	ds_read_b128 v[134:137], v134 offset:3072
	ds_read_b128 v[146:149], v158
	ds_read_b128 v[150:153], v158 offset:1024
	ds_read_b128 v[154:157], v158 offset:2048
	ds_read_b128 v[158:161], v158 offset:3072
	ds_read_b128 v[162:165], v186 offset:32768
	ds_read_b128 v[166:169], v186 offset:33792
	ds_read_b128 v[170:173], v186 offset:34816
	ds_read_b128 v[174:177], v186 offset:35840
	ds_read_b128 v[188:191], v186 offset:36864
	ds_read_b128 v[202:205], v186 offset:37888
	ds_read_b128 v[206:209], v186 offset:38912
	ds_read_b128 v[210:213], v186 offset:39936
	s_add_u32 s30, s60, 0x40000
	s_addc_u32 s31, s61, 0
	s_mov_b32 m0, s55
	s_nop 0
	global_load_lds_dwordx4 v0, s[30:31]
	s_nop 0
	s_mov_b32 m0, s88
	s_nop 0
	global_load_lds_dwordx4 v181, s[30:31]
	s_add_i32 s34, s91, 1
	s_cmp_ge_u32 s90, s26
	s_cselect_b32 s90, s34, s91
	s_xor_b32 s90, s90, s5
	s_sub_i32 s5, s90, s5
	s_lshl_b32 s90, s5, 3
	s_sub_i32 s91, 0x80, s90
	s_min_i32 s91, s91, 8
	s_abs_i32 s34, s91
	v_cvt_f32_u32_e32 v192, s34
	s_sub_i32 s36, 0, s34
	s_mul_i32 s5, s5, s26
	s_sub_i32 s4, s4, s5
	v_rcp_iflag_f32_e32 v192, v192
	s_abs_i32 s35, s4
	s_xor_b32 s5, s4, s91
	s_ashr_i32 s5, s5, 31
	v_mul_f32_e32 v192, 0x4f7ffffe, v192
	v_cvt_u32_f32_e32 v192, v192
	s_nop 0
	v_readfirstlane_b32 s37, v192
	s_mul_i32 s36, s36, s37
	s_mul_hi_u32 s36, s37, s36
	s_add_i32 s37, s37, s36
	s_mul_hi_u32 s36, s35, s37
	s_mul_i32 s37, s36, s34
	s_sub_i32 s35, s35, s37
	s_waitcnt vmcnt(8)
	s_waitcnt lgkmcnt(0)
	s_setprio 1
	s_barrier
	v_mfma_f32_16x16x32_bf16 v[142:145], v[74:77], v[162:165], v[142:145]
	v_mfma_f32_16x16x32_bf16 v[142:145], v[94:97], v[166:169], v[142:145]
	v_mfma_f32_16x16x32_bf16 v[138:141], v[114:117], v[162:165], v[138:141]
	v_mfma_f32_16x16x32_bf16 v[138:141], v[134:137], v[166:169], v[138:141]
	v_mfma_f32_16x16x32_bf16 v[130:133], v[146:149], v[162:165], v[130:133]
	v_mfma_f32_16x16x32_bf16 v[130:133], v[150:153], v[166:169], v[130:133]
	v_mfma_f32_16x16x32_bf16 v[126:129], v[154:157], v[162:165], v[126:129]
	v_mfma_f32_16x16x32_bf16 v[126:129], v[158:161], v[166:169], v[126:129]
	v_mfma_f32_16x16x32_bf16 v[106:109], v[154:157], v[170:173], v[106:109]
	v_mfma_f32_16x16x32_bf16 v[106:109], v[158:161], v[174:177], v[106:109]
	v_mfma_f32_16x16x32_bf16 v[110:113], v[146:149], v[170:173], v[110:113]
	v_mfma_f32_16x16x32_bf16 v[110:113], v[150:153], v[174:177], v[110:113]
	v_mfma_f32_16x16x32_bf16 v[118:121], v[114:117], v[170:173], v[118:121]
	v_mfma_f32_16x16x32_bf16 v[118:121], v[134:137], v[174:177], v[118:121]
	v_mfma_f32_16x16x32_bf16 v[122:125], v[74:77], v[170:173], v[122:125]
	v_mfma_f32_16x16x32_bf16 v[122:125], v[94:97], v[174:177], v[122:125]
	v_mfma_f32_16x16x32_bf16 v[102:105], v[74:77], v[188:191], v[102:105]
	v_mfma_f32_16x16x32_bf16 v[102:105], v[94:97], v[202:205], v[102:105]
	v_mfma_f32_16x16x32_bf16 v[98:101], v[114:117], v[188:191], v[98:101]
	v_mfma_f32_16x16x32_bf16 v[98:101], v[134:137], v[202:205], v[98:101]
	v_mfma_f32_16x16x32_bf16 v[90:93], v[146:149], v[188:191], v[90:93]
	v_mfma_f32_16x16x32_bf16 v[90:93], v[150:153], v[202:205], v[90:93]
	v_mfma_f32_16x16x32_bf16 v[86:89], v[154:157], v[188:191], v[86:89]
	v_mfma_f32_16x16x32_bf16 v[86:89], v[158:161], v[202:205], v[86:89]
	v_mfma_f32_16x16x32_bf16 v[66:69], v[154:157], v[206:209], v[66:69]
	v_mfma_f32_16x16x32_bf16 v[66:69], v[158:161], v[210:213], v[66:69]
	v_mfma_f32_16x16x32_bf16 v[70:73], v[146:149], v[206:209], v[70:73]
	v_mfma_f32_16x16x32_bf16 v[70:73], v[150:153], v[210:213], v[70:73]
	v_mfma_f32_16x16x32_bf16 v[78:81], v[114:117], v[206:209], v[78:81]
	v_mfma_f32_16x16x32_bf16 v[78:81], v[134:137], v[210:213], v[78:81]
	v_mfma_f32_16x16x32_bf16 v[82:85], v[74:77], v[206:209], v[82:85]
	v_mfma_f32_16x16x32_bf16 v[82:85], v[94:97], v[210:213], v[82:85]
	s_barrier
; #define PG8_STAGE(bufoff, gbase, voff) do { _Pragma("unroll") for (int _i = 0; _i < 2; ++_i) { \
;         const unsigned _m0 = ldsb + (unsigned)((bufoff) + _i * 8192); const char* _gb = (const char*)(gbase); \
;         asm volatile("s_mov_b32 m0, %0\n\ts_nop 0\n\tglobal_load_lds_dwordx4 %1, %2" :: "s"(_m0), "v"((voff)[_i]), "s"(_gb) : "m0", "memory"); } } while (0)
; #define PG8_LDA(dst, b, h) do { _Pragma("unroll") for (int m = 0; m < 4; ++m) _Pragma("unroll") for (int k = 0; k < 2; ++k) dst[m][k] = *(const LAS bf16x8*)(lds + PG8_SA(b, h) + aoff + m * 2048 + k * 1024); } while (0)
; #define PG8_MMA(ai, bj, At, Bt) do { __builtin_amdgcn_s_setprio(1); _Pragma("unroll") for (int m = 0; m < 4; ++m) _Pragma("unroll") for (int n = 0; n < 2; ++n) _Pragma("unroll") for (int k = 0; k < 2; ++k) \
;         acc[ai][bj][m][n] = __builtin_amdgcn_mfma_f32_16x16x32_bf16(Bt[n][k], At[m][k], acc[ai][bj][m][n], 0, 0, 0); __builtin_amdgcn_s_setprio(0); } while (0)
; #define PG8_WAIT_V(n) asm volatile("s_waitcnt vmcnt(" #n ")" ::: "memory")
; #define PG8_WAIT_L(n) asm volatile("s_waitcnt lgkmcnt(" #n ")" ::: "memory")
; #define PG8_BAR __builtin_amdgcn_s_barrier()
; #define PG8_SCHED __builtin_amdgcn_sched_barrier(0)
; template <class Epi, bool ALIGN_EPI>
; __device__ __forceinline__ void gemm_phase(LAS unsigned char* lds, const Gemm g, const StaticOrder& S, const Epi& E) {
;     ...
;         const bool has_next = S.next(ui + 1, nxt);
;         const char* nA = has_next ? (const char*)g.A + (size_t)nxt.pm * tstepA + (size_t)nxt.pn * g.a_pn_off * 2 + (size_t)(nxt.pm >> 4) * g.a_adj : cA; const char* nB = has_next ? (const char*)g.Bt + (size_t)nxt.pn * tstepB : cB;
;     ...
;             const char* a2 = last ? nA : cA + (size_t)(t + 2) * kstep; const char* b2 = last ? nB : cB + (size_t)(t + 2) * kstep;
;     ...
;             PG8_LDA(At, 1, 1); PG8_STAGE(PG8_SB(1, 0), b3, voffB); PG8_STAGE(PG8_SB(1, 1), b3 + hstepB, voffB); PG8_STAGE(PG8_SA(1, 0), a3, voffA);
;             PG8_WAIT_V(8); PG8_WAIT_L(0); PG8_BAR; PG8_MMA(1, 0, At, B0); PG8_MMA(1, 1, At, B1); PG8_BAR; PG8_SCHED;
	s_setprio 0
	ds_read_b128 v[162:165], v186 offset:49152
	ds_read_b128 v[166:169], v186 offset:50176
	ds_read_b128 v[170:173], v186 offset:51200
	ds_read_b128 v[174:177], v186 offset:52224
	ds_read_b128 v[188:191], v186 offset:53248
	ds_read_b128 v[202:205], v186 offset:54272
	ds_read_b128 v[206:209], v186 offset:55296
	ds_read_b128 v[210:213], v186 offset:56320
	s_add_u32 s30, s58, 0x80
	s_addc_u32 s31, s59, 0
	s_mov_b32 m0, s94
	s_nop 0
	global_load_lds_dwordx4 v180, s[30:31]
	s_nop 0
	s_mov_b32 m0, s95
	s_nop 0
	global_load_lds_dwordx4 v182, s[30:31]
	s_add_u32 s30, s58, 0x40080
	s_addc_u32 s31, s59, 0
	s_mov_b32 m0, s17
	s_nop 0
	global_load_lds_dwordx4 v180, s[30:31]
	s_nop 0
	s_mov_b32 m0, s53
	s_nop 0
	global_load_lds_dwordx4 v182, s[30:31]
	s_nop 0
	s_mov_b32 m0, s96
	s_nop 0
	global_load_lds_dwordx4 v0, s[56:57]
	s_nop 0
	s_mov_b32 m0, s97
	s_nop 0
	global_load_lds_dwordx4 v181, s[56:57]
	s_add_i32 s37, s36, 1
	s_sub_i32 s38, s35, s34
	s_cmp_ge_u32 s35, s34
	s_cselect_b32 s36, s37, s36
	s_cselect_b32 s35, s38, s35
	s_add_i32 s37, s36, 1
	s_cmp_ge_u32 s35, s34
	s_cselect_b32 s34, s37, s36
	s_xor_b32 s34, s34, s5
	s_sub_i32 s34, s34, s5
	s_mul_i32 s5, s34, s91
	s_sub_i32 s4, s4, s5
	s_add_i32 s36, s4, s90
	s_ashr_i32 s37, s36, 31
	s_lshl_b64 s[4:5], s[36:37], 19
	s_add_u32 s38, s18, s4
	s_addc_u32 s39, s19, s5
	s_and_b64 s[4:5], s[8:9], exec
	s_cselect_b32 s4, s39, s59
	s_cselect_b32 s5, s38, s58
	s_ashr_i32 s35, s34, 31
	s_lshl_b64 vcc, s[34:35], 19
	s_add_u32 s90, s1, vcc_lo
	s_addc_u32 s91, s14, vcc_hi
	s_and_b64 vcc, s[8:9], exec
	s_cselect_b32 s35, s91, s57
	s_cselect_b32 s37, s90, s56
	s_waitcnt vmcnt(8)
	s_waitcnt lgkmcnt(0)
	s_setprio 1
	s_barrier
	v_mfma_f32_16x16x32_bf16 v[62:65], v[74:77], v[162:165], v[62:65]
	v_mfma_f32_16x16x32_bf16 v[62:65], v[94:97], v[166:169], v[62:65]
	v_mfma_f32_16x16x32_bf16 v[58:61], v[114:117], v[162:165], v[58:61]
	v_mfma_f32_16x16x32_bf16 v[58:61], v[134:137], v[166:169], v[58:61]
	v_mfma_f32_16x16x32_bf16 v[54:57], v[146:149], v[162:165], v[54:57]
	v_mfma_f32_16x16x32_bf16 v[54:57], v[150:153], v[166:169], v[54:57]
	v_mfma_f32_16x16x32_bf16 v[50:53], v[154:157], v[162:165], v[50:53]
	v_mfma_f32_16x16x32_bf16 v[50:53], v[158:161], v[166:169], v[50:53]
	v_mfma_f32_16x16x32_bf16 v[34:37], v[154:157], v[170:173], v[34:37]
	v_mfma_f32_16x16x32_bf16 v[34:37], v[158:161], v[174:177], v[34:37]
	v_mfma_f32_16x16x32_bf16 v[38:41], v[146:149], v[170:173], v[38:41]
	v_mfma_f32_16x16x32_bf16 v[38:41], v[150:153], v[174:177], v[38:41]
	v_mfma_f32_16x16x32_bf16 v[42:45], v[114:117], v[170:173], v[42:45]
	v_mfma_f32_16x16x32_bf16 v[42:45], v[134:137], v[174:177], v[42:45]
	v_mfma_f32_16x16x32_bf16 v[46:49], v[74:77], v[170:173], v[46:49]
	v_mfma_f32_16x16x32_bf16 v[46:49], v[94:97], v[174:177], v[46:49]
	v_mfma_f32_16x16x32_bf16 v[30:33], v[74:77], v[188:191], v[30:33]
	v_mfma_f32_16x16x32_bf16 v[30:33], v[94:97], v[202:205], v[30:33]
	v_mfma_f32_16x16x32_bf16 v[26:29], v[114:117], v[188:191], v[26:29]
	v_mfma_f32_16x16x32_bf16 v[26:29], v[134:137], v[202:205], v[26:29]
	v_mfma_f32_16x16x32_bf16 v[22:25], v[146:149], v[188:191], v[22:25]
	v_mfma_f32_16x16x32_bf16 v[22:25], v[150:153], v[202:205], v[22:25]
	v_mfma_f32_16x16x32_bf16 v[18:21], v[154:157], v[188:191], v[18:21]
	v_mfma_f32_16x16x32_bf16 v[18:21], v[158:161], v[202:205], v[18:21]
	v_mfma_f32_16x16x32_bf16 v[2:5], v[154:157], v[206:209], v[2:5]
	v_mfma_f32_16x16x32_bf16 v[2:5], v[158:161], v[210:213], v[2:5]
	v_mfma_f32_16x16x32_bf16 v[6:9], v[146:149], v[206:209], v[6:9]
	v_mfma_f32_16x16x32_bf16 v[6:9], v[150:153], v[210:213], v[6:9]
	v_mfma_f32_16x16x32_bf16 v[10:13], v[114:117], v[206:209], v[10:13]
	v_mfma_f32_16x16x32_bf16 v[10:13], v[134:137], v[210:213], v[10:13]
	v_mfma_f32_16x16x32_bf16 v[14:17], v[74:77], v[206:209], v[14:17]
	v_mfma_f32_16x16x32_bf16 v[14:17], v[94:97], v[210:213], v[14:17]
	s_barrier
	s_setprio 0
	s_add_i32 s50, s50, 2
	s_add_u32 s41, s41, 0x100
	s_addc_u32 s49, s49, 0
	s_add_u32 s92, s92, 0x100
	s_addc_u32 s93, s93, 0
	s_cmp_gt_u32 s50, 13

; __device__ __forceinline__ float rstd_of(const float* ss, int row) { const f32x4 p = *(const f32x4*)(ss + 4 * (size_t)row); return __builtin_amdgcn_rsqf(((p.x + p.y) + (p.z + p.w)) * (1.0f / D) + EPS); }
; __device__ __forceinline__ float silu_f(float g) { return g * __builtin_amdgcn_rcpf(1.0f + __builtin_amdgcn_exp2f(g * -1.4426950408889634f)); }
; __device__ __forceinline__ void rstd8(const float* ss, int row0, float (&rs)[2][4]) {
;     f32x4 p[2][4];
; #pragma unroll
;     for (int ai = 0; ai < 2; ++ai)
; #pragma unroll
;         for (int m = 0; m < 4; ++m) p[ai][m] = *(const f32x4*)(ss + 4 * (size_t)(row0 + ai * HALF + m * 16));
; #pragma unroll
;     for (int ai = 0; ai < 2; ++ai)
; #pragma unroll
;         for (int m = 0; m < 4; ++m) rs[ai][m] = __builtin_amdgcn_rsqf(((p[ai][m].x + p[ai][m].y) + (p[ai][m].z + p[ai][m].w)) * (1.0f / D) + EPS);
;     __device__ __forceinline__ void operator()(const f32x4 (&acc)[2][2][4][2], const Unit& u, int wr, int wc, int fr, int fq) const {
;         const int row0 = u.pm * BM + wr * 64 + fr, col0 = u.pn * HALF + wc * 32 + 8 * fq;
;         float rsv[2][4]; rstd8(ss, row0, rsv);
.Lep_fast:
	s_lshl_b32 s4, s54, 8
	s_add_i32 s4, s4, s89
	v_or_b32_e32 v178, s4, v183
	s_lshl_b32 s5, s0, 1
	v_lshl_or_b32 v179, s48, 7, v184
	s_lshl_b32 s30, s5, 4
	s_mul_i32 s31, s5, 80
	v_mul_lo_u32 v190, v178, s5
	s_cmp_eq_u32 s54, s98
	v_lshl_add_u32 v190, v179, 1, v190
	s_cbranch_scc1 .Lep_have_rs
	s_lshl_b32 s4, s89, 4
	s_add_i32 s4, s4, 0x23000
	v_lshl_add_u32 v178, v183, 4, s4
	ds_read_b128 v[146:149], v178
	ds_read_b128 v[150:153], v178 offset:256
	ds_read_b128 v[154:157], v178 offset:512
	ds_read_b128 v[158:161], v178 offset:768
	ds_read_b128 v[162:165], v178 offset:2048
	ds_read_b128 v[166:169], v178 offset:2304
	ds_read_b128 v[170:173], v178 offset:2560
	ds_read_b128 v[174:177], v178 offset:2816
	s_mov_b32 s98, s54
	s_waitcnt lgkmcnt(0)
	v_add_f32_e32 v146, v146, v147
	v_add_f32_e32 v148, v148, v149
	v_add_f32_e32 v150, v150, v151
	v_add_f32_e32 v152, v152, v153
	v_add_f32_e32 v154, v154, v155
	v_add_f32_e32 v156, v156, v157
	v_add_f32_e32 v158, v158, v159
	v_add_f32_e32 v160, v160, v161
	v_add_f32_e32 v162, v162, v163
	v_add_f32_e32 v164, v164, v165
	v_add_f32_e32 v166, v166, v167
	v_add_f32_e32 v168, v168, v169
	v_add_f32_e32 v170, v170, v171
	v_add_f32_e32 v172, v172, v173
	v_add_f32_e32 v174, v174, v175
	v_add_f32_e32 v176, v176, v177
	v_add_f32_e32 v146, v146, v148
	v_add_f32_e32 v150, v150, v152
	v_add_f32_e32 v154, v154, v156
	v_add_f32_e32 v158, v158, v160
	v_add_f32_e32 v162, v162, v164
	v_add_f32_e32 v166, v166, v168
	v_add_f32_e32 v170, v170, v172
	v_add_f32_e32 v174, v174, v176
	v_fmamk_f32 v241, v146, 0x3a800000, v224
	v_fmamk_f32 v243, v150, 0x3a800000, v224
	v_fmamk_f32 v245, v154, 0x3a800000, v224
	v_fmamk_f32 v247, v158, 0x3a800000, v224
	v_fmamk_f32 v249, v162, 0x3a800000, v224
	v_fmamk_f32 v251, v166, 0x3a800000, v224
	v_fmamk_f32 v253, v170, 0x3a800000, v224
	v_fmamk_f32 v215, v174, 0x3a800000, v224
	v_rsq_f32_e32 v240, v241
	v_rsq_f32_e32 v242, v243
	v_rsq_f32_e32 v244, v245
	v_rsq_f32_e32 v246, v247
	v_rsq_f32_e32 v248, v249
	v_rsq_f32_e32 v250, v251
	v_rsq_f32_e32 v252, v253
	v_rsq_f32_e32 v214, v215
	s_nop 0
	v_mul_f32_e32 v240, 0xbfb8aa3b, v240
	v_mul_f32_e32 v242, 0xbfb8aa3b, v242
	v_mul_f32_e32 v244, 0xbfb8aa3b, v244
	v_mul_f32_e32 v246, 0xbfb8aa3b, v246
	v_mul_f32_e32 v248, 0xbfb8aa3b, v248
	v_mul_f32_e32 v250, 0xbfb8aa3b, v250
	v_mul_f32_e32 v252, 0xbfb8aa3b, v252
	v_mul_f32_e32 v214, 0xbfb8aa3b, v214
